# cache-policy hint: nt on the read-once row loads of all modulated-norm loops (P1 both variants, P8)
# baseline (speedup 1.0000x reference)
.LBB0_240:
	v_add_u32_e32 v108, -3, v92
	v_mul_hi_i32 v2, v108, s71
	v_lshrrev_b32_e32 v3, 31, v2
	v_ashrrev_i32_e32 v2, 9, v2
	v_add_u32_e32 v50, v2, v3
	v_mad_i32_i24 v101, v50, s73, v92
	v_add_u32_e32 v99, -3, v101
	s_movk_i32 s0, 0x100
	v_cmp_gt_i32_e64 s[0:1], s0, v99
	v_add_u32_e32 v106, -2, v92
	v_add_u32_e32 v104, -1, v92
	v_cndmask_b32_e64 v2, v50, 32, s[0:1]
	v_add_u32_e32 v2, s66, v2
	v_mul_i32_i24_e32 v2, 6, v2
	v_ashrrev_i32_e32 v3, 31, v2
	v_lshlrev_b64 v[2:3], 12, v[2:3]
	v_lshl_add_u64 v[112:113], s[24:25], 0, v[2:3]
	s_mov_b64 s[12:13], 0x1000
	s_mov_b64 s[10:11], -1
	s_and_b64 vcc, exec, s[34:35]
	v_ashrrev_i32_e32 v109, 31, v108
	v_ashrrev_i32_e32 v93, 31, v92
	v_lshl_add_u64 v[110:111], v[112:113], 0, s[12:13]
	v_ashrrev_i32_e32 v107, 31, v106
	v_ashrrev_i32_e32 v105, 31, v104
	s_cbranch_vccz .LBB0_242
	v_lshlrev_b64 v[74:75], 11, v[108:109]
	v_lshl_add_u64 v[2:3], v[82:83], 0, v[74:75]
	v_lshlrev_b64 v[72:73], 11, v[106:107]
	global_load_dwordx4 v[46:49], v[2:3], off nt
	global_load_dwordx4 v[42:45], v[2:3], off offset:1024 nt
	v_lshl_add_u64 v[2:3], v[82:83], 0, v[72:73]
	v_lshlrev_b64 v[70:71], 11, v[104:105]
	global_load_dwordx4 v[38:41], v[2:3], off nt
	global_load_dwordx4 v[34:37], v[2:3], off offset:1024 nt
	v_lshl_add_u64 v[2:3], v[82:83], 0, v[70:71]
	v_lshlrev_b64 v[52:53], 11, v[92:93]
	v_mov_b32_e32 v95, v1
	global_load_dwordx4 v[30:33], v[2:3], off nt
	global_load_dwordx4 v[26:29], v[2:3], off offset:1024 nt
	v_lshl_add_u64 v[2:3], v[82:83], 0, v[52:53]
	v_lshl_add_u64 v[66:67], v[112:113], 0, v[94:95]
	v_lshl_add_u64 v[58:59], v[110:111], 0, v[94:95]
	global_load_dwordx4 v[22:25], v[2:3], off nt
	global_load_dwordx4 v[18:21], v[2:3], off offset:1024 nt
	s_nop 0
	global_load_dwordx4 v[2:5], v[86:87], off offset:16
	global_load_dwordx4 v[10:13], v[86:87], off
	global_load_dwordx4 v[6:9], v[66:67], off offset:16
	global_load_dwordx4 v[14:17], v[66:67], off
	global_load_dwordx4 v[54:57], v[58:59], off offset:16
	s_nop 0
	global_load_dwordx4 v[58:61], v[58:59], off
	v_mov_b32_e32 v97, v1
	v_cmp_lt_i32_e32 vcc, v228, v225
	v_lshl_add_u64 v[74:75], v[84:85], 0, v[74:75]
	v_lshl_add_u64 v[72:73], v[84:85], 0, v[72:73]
	v_cndmask_b32_e32 v51, v224, v228, vcc
	v_cmp_lt_i32_e32 vcc, v227, v225
	v_lshlrev_b32_e32 v118, 2, v51
	s_mov_b64 s[10:11], 0
	v_cndmask_b32_e32 v51, v224, v227, vcc
	v_cmp_lt_i32_e32 vcc, v226, v225
	v_lshlrev_b32_e32 v103, 2, v51
	s_waitcnt vmcnt(0)
	v_pk_add_f32 v[60:61], v[60:61], 1.0 op_sel_hi:[1,0]
	v_pk_add_f32 v[62:63], v[58:59], 1.0 op_sel_hi:[1,0]
	v_pk_mul_f32 v[58:59], v[12:13], v[60:61]
	v_pk_mul_f32 v[60:61], v[10:11], v[62:63]
	v_pk_add_f32 v[10:11], v[56:57], 1.0 op_sel_hi:[1,0]
	v_pk_add_f32 v[12:13], v[54:55], 1.0 op_sel_hi:[1,0]
	v_pk_mul_f32 v[54:55], v[4:5], v[10:11]
	v_pk_mul_f32 v[56:57], v[2:3], v[12:13]
	global_load_dwordx4 v[76:79], v[86:87], off offset:2064
	global_load_dwordx4 v[62:65], v[86:87], off offset:2048
	global_load_dwordx4 v[2:5], v[66:67], off offset:2064
	global_load_dwordx4 v[10:13], v[66:67], off offset:2048
	v_lshl_add_u64 v[66:67], v[110:111], 0, v[96:97]
	global_load_dwordx4 v[114:117], v[66:67], off offset:16
	s_nop 0
	global_load_dwordx4 v[66:69], v[66:67], off
	v_cndmask_b32_e32 v51, v224, v226, vcc
	v_lshlrev_b32_e32 v97, 2, v51
	v_xor_b32_e32 v51, 4, v224
	v_cmp_lt_i32_e32 vcc, v51, v225
	s_waitcnt vmcnt(0)
	v_pk_add_f32 v[68:69], v[68:69], 1.0 op_sel_hi:[1,0]
	v_cndmask_b32_e32 v51, v224, v51, vcc
	v_pk_add_f32 v[80:81], v[66:67], 1.0 op_sel_hi:[1,0]
	v_pk_mul_f32 v[66:67], v[64:65], v[68:69]
	v_pk_add_f32 v[64:65], v[114:115], 1.0 op_sel_hi:[1,0]
	v_lshlrev_b32_e32 v95, 2, v51
	v_xor_b32_e32 v51, 2, v224
	v_pk_mul_f32 v[68:69], v[62:63], v[80:81]
	v_pk_add_f32 v[62:63], v[116:117], 1.0 op_sel_hi:[1,0]
	v_pk_mul_f32 v[64:65], v[76:77], v[64:65]
	v_cmp_lt_i32_e32 vcc, v51, v225
	v_xor_b32_e32 v76, 1, v224
	v_and_b32_e32 v81, 0xffff0000, v48
	v_and_b32_e32 v80, 0xffff0000, v46
	v_pk_mul_f32 v[62:63], v[78:79], v[62:63]
	v_cndmask_b32_e32 v51, v224, v51, vcc
	v_cmp_lt_i32_e32 vcc, v76, v225
	v_lshlrev_b32_e32 v79, 16, v48
	v_lshlrev_b32_e32 v78, 16, v46
	v_lshlrev_b32_e32 v114, 16, v47
	v_and_b32_e32 v116, 0xffff0000, v47
	v_pk_mul_f32 v[46:47], v[80:81], v[80:81]
	v_cndmask_b32_e32 v76, v224, v76, vcc
	v_lshlrev_b32_e32 v115, 16, v49
	v_pk_fma_f32 v[46:47], v[78:79], v[78:79], v[46:47]
	v_lshlrev_b32_e32 v119, 2, v76
	v_and_b32_e32 v117, 0xffff0000, v49
	v_pk_fma_f32 v[46:47], v[114:115], v[114:115], v[46:47]
	v_and_b32_e32 v77, 0xffff0000, v42
	v_and_b32_e32 v76, 0xffff0000, v44
	v_pk_fma_f32 v[120:121], v[116:117], v[116:117], v[46:47]
	v_lshlrev_b32_e32 v47, 16, v42
	v_lshlrev_b32_e32 v46, 16, v44
	v_lshlrev_b32_e32 v48, 16, v45
	v_and_b32_e32 v42, 0xffff0000, v45
	v_pk_mul_f32 v[44:45], v[76:77], v[76:77]
	v_lshlrev_b32_e32 v49, 16, v43
	v_pk_fma_f32 v[44:45], v[46:47], v[46:47], v[44:45]
	v_and_b32_e32 v43, 0xffff0000, v43
	v_pk_fma_f32 v[44:45], v[48:49], v[48:49], v[44:45]
	v_add_f32_e32 v120, v120, v121
	v_pk_fma_f32 v[44:45], v[42:43], v[42:43], v[44:45]
	v_lshlrev_b32_e32 v51, 2, v51
	v_add_f32_e32 v45, v120, v45
	v_add_f32_e32 v44, v44, v45
	ds_bpermute_b32 v45, v118, v44
	v_mov_b32_e32 v121, v80
	v_mov_b32_e32 v123, v116
	v_mov_b32_e32 v80, v79
	v_mov_b32_e32 v116, v115
	s_waitcnt lgkmcnt(0)
	v_add_f32_e32 v44, v44, v45
	ds_bpermute_b32 v45, v103, v44
	v_mov_b32_e32 v120, v78
	v_mov_b32_e32 v122, v114
	s_waitcnt lgkmcnt(0)
	v_add_f32_e32 v44, v44, v45
	ds_bpermute_b32 v45, v97, v44
	s_waitcnt lgkmcnt(0)
	v_add_f32_e32 v44, v44, v45
	ds_bpermute_b32 v45, v95, v44
	s_waitcnt lgkmcnt(0)
	v_add_f32_e32 v44, v44, v45
	ds_bpermute_b32 v45, v51, v44
	s_waitcnt lgkmcnt(0)
	v_add_f32_e32 v44, v44, v45
	ds_bpermute_b32 v45, v119, v44
	s_waitcnt lgkmcnt(0)
	v_add_f32_e32 v44, v44, v45
	v_fmamk_f32 v44, v44, 0x3a800000, v220
	v_cmp_gt_f32_e32 vcc, s93, v44
	v_mul_f32_e32 v45, 0x4b800000, v44
	s_nop 0
	v_cndmask_b32_e32 v44, v44, v45, vcc
	v_rsq_f32_e32 v44, v44
	s_nop 0
	v_mul_f32_e32 v45, 0x45800000, v44
	v_cndmask_b32_e32 v44, v44, v45, vcc
	v_pk_mul_f32 v[78:79], v[44:45], v[80:81] op_sel_hi:[0,1]
	v_pk_mul_f32 v[80:81], v[44:45], v[116:117] op_sel_hi:[0,1]
	v_pk_mul_f32 v[120:121], v[44:45], v[120:121] op_sel_hi:[0,1]
	v_pk_mul_f32 v[122:123], v[44:45], v[122:123] op_sel_hi:[0,1]
	v_pk_fma_f32 v[114:115], v[54:55], v[80:81], v[8:9]
	v_pk_fma_f32 v[80:81], v[56:57], v[78:79], v[6:7]
	v_pk_fma_f32 v[122:123], v[58:59], v[122:123], v[16:17]
	v_pk_fma_f32 v[120:121], v[60:61], v[120:121], v[14:15]
	s_nop 0
	v_cvt_pk_bf16_f32 v78, v120, v121
	v_cvt_pk_bf16_f32 v79, v122, v123
	v_cvt_pk_bf16_f32 v80, v80, v81
	v_cvt_pk_bf16_f32 v81, v114, v115
	global_store_dwordx4 v[74:75], v[78:81], off
	s_nop 1
	v_mov_b32_e32 v78, v47
	v_mov_b32_e32 v79, v77
	v_mov_b32_e32 v80, v49
	v_mov_b32_e32 v81, v43
	v_mov_b32_e32 v47, v76
	v_mov_b32_e32 v49, v42
	v_pk_mul_f32 v[78:79], v[44:45], v[78:79] op_sel_hi:[0,1]
	v_pk_mul_f32 v[80:81], v[44:45], v[80:81] op_sel_hi:[0,1]
	v_pk_mul_f32 v[46:47], v[44:45], v[46:47] op_sel_hi:[0,1]
	v_pk_mul_f32 v[42:43], v[44:45], v[48:49] op_sel_hi:[0,1]
	v_pk_fma_f32 v[80:81], v[66:67], v[80:81], v[12:13]
	v_pk_fma_f32 v[78:79], v[68:69], v[78:79], v[10:11]
	v_pk_fma_f32 v[48:49], v[62:63], v[42:43], v[4:5]
	v_pk_fma_f32 v[44:45], v[64:65], v[46:47], v[2:3]
	v_cvt_pk_bf16_f32 v42, v78, v79
	v_cvt_pk_bf16_f32 v43, v80, v81
	v_lshlrev_b32_e32 v46, 16, v39
	v_cvt_pk_bf16_f32 v44, v44, v45
	v_cvt_pk_bf16_f32 v45, v48, v49
	global_store_dwordx4 v[74:75], v[42:45], off offset:1024
	v_and_b32_e32 v75, 0xffff0000, v34
	v_and_b32_e32 v74, 0xffff0000, v36
	v_and_b32_e32 v43, 0xffff0000, v40
	v_and_b32_e32 v42, 0xffff0000, v38
	v_lshlrev_b32_e32 v45, 16, v40
	v_lshlrev_b32_e32 v44, 16, v38
	v_and_b32_e32 v40, 0xffff0000, v39
	v_pk_mul_f32 v[38:39], v[42:43], v[42:43]
	v_lshlrev_b32_e32 v47, 16, v41
	v_pk_fma_f32 v[38:39], v[44:45], v[44:45], v[38:39]
	v_lshlrev_b32_e32 v49, 16, v34
	v_lshlrev_b32_e32 v48, 16, v36
	v_lshlrev_b32_e32 v77, 16, v35
	v_and_b32_e32 v79, 0xffff0000, v35
	v_pk_mul_f32 v[34:35], v[74:75], v[74:75]
	v_and_b32_e32 v41, 0xffff0000, v41
	v_pk_fma_f32 v[38:39], v[46:47], v[46:47], v[38:39]
	v_lshlrev_b32_e32 v76, 16, v37
	v_pk_fma_f32 v[34:35], v[48:49], v[48:49], v[34:35]
	v_pk_fma_f32 v[38:39], v[40:41], v[40:41], v[38:39]
	v_and_b32_e32 v78, 0xffff0000, v37
	v_pk_fma_f32 v[34:35], v[76:77], v[76:77], v[34:35]
	v_add_f32_e32 v36, v38, v39
	v_pk_fma_f32 v[34:35], v[78:79], v[78:79], v[34:35]
	v_mov_b32_e32 v37, v40
	v_add_f32_e32 v35, v36, v35
	v_add_f32_e32 v34, v34, v35
	ds_bpermute_b32 v35, v118, v34
	v_mov_b32_e32 v36, v46
	v_mov_b32_e32 v40, v47
	v_and_b32_e32 v47, 0xffff0000, v27
	v_and_b32_e32 v46, 0xffff0000, v29
	s_waitcnt lgkmcnt(0)
	v_add_f32_e32 v34, v34, v35
	ds_bpermute_b32 v35, v103, v34
	s_waitcnt lgkmcnt(0)
	v_add_f32_e32 v34, v34, v35
	ds_bpermute_b32 v35, v97, v34
	s_waitcnt lgkmcnt(0)
	v_add_f32_e32 v34, v34, v35
	ds_bpermute_b32 v35, v95, v34
	s_waitcnt lgkmcnt(0)
	v_add_f32_e32 v34, v34, v35
	ds_bpermute_b32 v35, v51, v34
	s_waitcnt lgkmcnt(0)
	v_add_f32_e32 v34, v34, v35
	ds_bpermute_b32 v35, v119, v34
	s_waitcnt lgkmcnt(0)
	v_add_f32_e32 v34, v34, v35
	v_fmamk_f32 v34, v34, 0x3a800000, v220
	v_cmp_gt_f32_e32 vcc, s93, v34
	v_mul_f32_e32 v35, 0x4b800000, v34
	s_nop 0
	v_cndmask_b32_e32 v34, v34, v35, vcc
	v_rsq_f32_e32 v34, v34
	s_nop 0
	v_mul_f32_e32 v35, 0x45800000, v34
	v_cndmask_b32_e32 v38, v34, v35, vcc
	v_mov_b32_e32 v34, v44
	v_mov_b32_e32 v35, v42
	v_pk_mul_f32 v[34:35], v[38:39], v[34:35] op_sel_hi:[0,1]
	v_pk_mul_f32 v[36:37], v[38:39], v[36:37] op_sel_hi:[0,1]
	v_mov_b32_e32 v42, v45
	v_pk_fma_f32 v[36:37], v[58:59], v[36:37], v[16:17]
	v_pk_fma_f32 v[34:35], v[60:61], v[34:35], v[14:15]
	v_pk_mul_f32 v[42:43], v[38:39], v[42:43] op_sel_hi:[0,1]
	v_pk_mul_f32 v[40:41], v[38:39], v[40:41] op_sel_hi:[0,1]
	v_pk_fma_f32 v[40:41], v[54:55], v[40:41], v[8:9]
	v_pk_fma_f32 v[42:43], v[56:57], v[42:43], v[6:7]
	v_cvt_pk_bf16_f32 v34, v34, v35
	v_cvt_pk_bf16_f32 v35, v36, v37
	v_lshlrev_b32_e32 v45, 16, v27
	v_cvt_pk_bf16_f32 v36, v42, v43
	v_cvt_pk_bf16_f32 v37, v40, v41
	global_store_dwordx4 v[72:73], v[34:37], off
	v_and_b32_e32 v43, 0xffff0000, v26
	v_and_b32_e32 v42, 0xffff0000, v28
	v_mov_b32_e32 v34, v49
	v_mov_b32_e32 v35, v75
	v_mov_b32_e32 v36, v77
	v_mov_b32_e32 v37, v79
	v_pk_mul_f32 v[34:35], v[38:39], v[34:35] op_sel_hi:[0,1]
	v_pk_mul_f32 v[36:37], v[38:39], v[36:37] op_sel_hi:[0,1]
	v_mov_b32_e32 v49, v74
	v_mov_b32_e32 v77, v78
	v_pk_fma_f32 v[36:37], v[66:67], v[36:37], v[12:13]
	v_pk_fma_f32 v[34:35], v[68:69], v[34:35], v[10:11]
	v_pk_mul_f32 v[40:41], v[38:39], v[48:49] op_sel_hi:[0,1]
	v_pk_mul_f32 v[38:39], v[38:39], v[76:77] op_sel_hi:[0,1]
	v_pk_fma_f32 v[38:39], v[62:63], v[38:39], v[4:5]
	v_pk_fma_f32 v[40:41], v[64:65], v[40:41], v[2:3]
	v_cvt_pk_bf16_f32 v34, v34, v35
	v_cvt_pk_bf16_f32 v35, v36, v37
	v_lshlrev_b32_e32 v44, 16, v29
	v_cvt_pk_bf16_f32 v36, v40, v41
	v_cvt_pk_bf16_f32 v37, v38, v39
	global_store_dwordx4 v[72:73], v[34:37], off offset:1024
	v_lshlrev_b32_e32 v38, 16, v31
	v_lshlrev_b32_e32 v39, 16, v33
	v_and_b32_e32 v37, 0xffff0000, v32
	v_and_b32_e32 v36, 0xffff0000, v30
	v_lshlrev_b32_e32 v35, 16, v32
	v_lshlrev_b32_e32 v34, 16, v30
	v_and_b32_e32 v32, 0xffff0000, v31
	v_pk_mul_f32 v[30:31], v[36:37], v[36:37]
	v_lshlrev_b32_e32 v41, 16, v26
	v_pk_fma_f32 v[30:31], v[34:35], v[34:35], v[30:31]
	v_lshlrev_b32_e32 v40, 16, v28
	v_pk_mul_f32 v[26:27], v[42:43], v[42:43]
	v_and_b32_e32 v33, 0xffff0000, v33
	v_pk_fma_f32 v[30:31], v[38:39], v[38:39], v[30:31]
	v_pk_fma_f32 v[26:27], v[40:41], v[40:41], v[26:27]
	v_pk_fma_f32 v[30:31], v[32:33], v[32:33], v[30:31]
	v_pk_fma_f32 v[26:27], v[44:45], v[44:45], v[26:27]
	v_add_f32_e32 v28, v30, v31
	v_pk_fma_f32 v[26:27], v[46:47], v[46:47], v[26:27]
	v_mov_b32_e32 v29, v32
	v_add_f32_e32 v27, v28, v27
	v_add_f32_e32 v26, v26, v27
	ds_bpermute_b32 v27, v118, v26
	v_mov_b32_e32 v28, v38
	v_mov_b32_e32 v32, v39
	v_lshl_add_u64 v[48:49], v[84:85], 0, v[70:71]
	s_waitcnt lgkmcnt(0)
	v_add_f32_e32 v26, v26, v27
	ds_bpermute_b32 v27, v103, v26
	s_waitcnt lgkmcnt(0)
	v_add_f32_e32 v26, v26, v27
	ds_bpermute_b32 v27, v97, v26
	s_waitcnt lgkmcnt(0)
	v_add_f32_e32 v26, v26, v27
	ds_bpermute_b32 v27, v95, v26
	s_waitcnt lgkmcnt(0)
	v_add_f32_e32 v26, v26, v27
	ds_bpermute_b32 v27, v51, v26
	s_waitcnt lgkmcnt(0)
	v_add_f32_e32 v26, v26, v27
	ds_bpermute_b32 v27, v119, v26
	s_waitcnt lgkmcnt(0)
	v_add_f32_e32 v26, v26, v27
	v_fmamk_f32 v26, v26, 0x3a800000, v220
	v_cmp_gt_f32_e32 vcc, s93, v26
	v_mul_f32_e32 v27, 0x4b800000, v26
	s_nop 0
	v_cndmask_b32_e32 v26, v26, v27, vcc
	v_rsq_f32_e32 v26, v26
	s_nop 0
	v_mul_f32_e32 v27, 0x45800000, v26
	v_cndmask_b32_e32 v30, v26, v27, vcc
	v_mov_b32_e32 v26, v34
	v_mov_b32_e32 v27, v36
	v_pk_mul_f32 v[26:27], v[30:31], v[26:27] op_sel_hi:[0,1]
	v_pk_mul_f32 v[28:29], v[30:31], v[28:29] op_sel_hi:[0,1]
	v_mov_b32_e32 v36, v35
	v_pk_fma_f32 v[28:29], v[58:59], v[28:29], v[16:17]
	v_pk_fma_f32 v[26:27], v[60:61], v[26:27], v[14:15]
	v_pk_mul_f32 v[34:35], v[30:31], v[36:37] op_sel_hi:[0,1]
	v_pk_mul_f32 v[32:33], v[30:31], v[32:33] op_sel_hi:[0,1]
	v_pk_fma_f32 v[32:33], v[54:55], v[32:33], v[8:9]
	v_pk_fma_f32 v[34:35], v[56:57], v[34:35], v[6:7]
	v_cvt_pk_bf16_f32 v26, v26, v27
	v_cvt_pk_bf16_f32 v27, v28, v29
	v_lshlrev_b32_e32 v36, 16, v21
	v_cvt_pk_bf16_f32 v28, v34, v35
	v_cvt_pk_bf16_f32 v29, v32, v33
	global_store_dwordx4 v[48:49], v[26:29], off
	v_and_b32_e32 v35, 0xffff0000, v18
	v_and_b32_e32 v34, 0xffff0000, v20
	v_mov_b32_e32 v26, v41
	v_mov_b32_e32 v27, v43
	v_mov_b32_e32 v28, v45
	v_mov_b32_e32 v29, v47
	v_pk_mul_f32 v[26:27], v[30:31], v[26:27] op_sel_hi:[0,1]
	v_pk_mul_f32 v[28:29], v[30:31], v[28:29] op_sel_hi:[0,1]
	v_mov_b32_e32 v41, v42
	v_mov_b32_e32 v45, v46
	v_pk_fma_f32 v[28:29], v[66:67], v[28:29], v[12:13]
	v_pk_fma_f32 v[26:27], v[68:69], v[26:27], v[10:11]
	v_pk_mul_f32 v[32:33], v[30:31], v[40:41] op_sel_hi:[0,1]
	v_pk_mul_f32 v[30:31], v[30:31], v[44:45] op_sel_hi:[0,1]
	v_pk_fma_f32 v[30:31], v[62:63], v[30:31], v[4:5]
	v_pk_fma_f32 v[32:33], v[64:65], v[32:33], v[2:3]
	v_cvt_pk_bf16_f32 v26, v26, v27
	v_cvt_pk_bf16_f32 v27, v28, v29
	v_lshlrev_b32_e32 v37, 16, v19
	v_cvt_pk_bf16_f32 v28, v32, v33
	v_cvt_pk_bf16_f32 v29, v30, v31
	global_store_dwordx4 v[48:49], v[26:29], off offset:1024
	v_lshlrev_b32_e32 v30, 16, v23
	v_lshlrev_b32_e32 v31, 16, v25
	v_and_b32_e32 v29, 0xffff0000, v24
	v_and_b32_e32 v28, 0xffff0000, v22
	v_lshlrev_b32_e32 v27, 16, v24
	v_lshlrev_b32_e32 v26, 16, v22
	v_and_b32_e32 v24, 0xffff0000, v23
	v_pk_mul_f32 v[22:23], v[28:29], v[28:29]
	v_lshlrev_b32_e32 v33, 16, v18
	v_pk_fma_f32 v[22:23], v[26:27], v[26:27], v[22:23]
	v_lshlrev_b32_e32 v32, 16, v20
	v_and_b32_e32 v18, 0xffff0000, v21
	v_pk_mul_f32 v[20:21], v[34:35], v[34:35]
	v_and_b32_e32 v25, 0xffff0000, v25
	v_pk_fma_f32 v[22:23], v[30:31], v[30:31], v[22:23]
	v_pk_fma_f32 v[20:21], v[32:33], v[32:33], v[20:21]
	v_pk_fma_f32 v[22:23], v[24:25], v[24:25], v[22:23]
	v_and_b32_e32 v19, 0xffff0000, v19
	v_pk_fma_f32 v[20:21], v[36:37], v[36:37], v[20:21]
	v_add_f32_e32 v22, v22, v23
	v_pk_fma_f32 v[20:21], v[18:19], v[18:19], v[20:21]
	v_mov_b32_e32 v39, v28
	v_add_f32_e32 v21, v22, v21
	v_add_f32_e32 v20, v20, v21
	ds_bpermute_b32 v21, v118, v20
	v_mov_b32_e32 v41, v24
	v_mov_b32_e32 v28, v27
	v_mov_b32_e32 v24, v31
	v_mov_b32_e32 v38, v26
	s_waitcnt lgkmcnt(0)
	v_add_f32_e32 v20, v20, v21
	ds_bpermute_b32 v21, v103, v20
	v_mov_b32_e32 v40, v30
	v_lshl_add_u64 v[22:23], v[84:85], 0, v[52:53]
	s_waitcnt lgkmcnt(0)
	v_add_f32_e32 v20, v20, v21
	ds_bpermute_b32 v21, v97, v20
	s_waitcnt lgkmcnt(0)
	v_add_f32_e32 v20, v20, v21
	ds_bpermute_b32 v21, v95, v20
	s_waitcnt lgkmcnt(0)
	v_add_f32_e32 v20, v20, v21
	ds_bpermute_b32 v21, v51, v20
	s_waitcnt lgkmcnt(0)
	v_add_f32_e32 v20, v20, v21
	ds_bpermute_b32 v21, v119, v20
	s_waitcnt lgkmcnt(0)
	v_add_f32_e32 v20, v20, v21
	v_fmamk_f32 v20, v20, 0x3a800000, v220
	v_cmp_gt_f32_e32 vcc, s93, v20
	v_mul_f32_e32 v21, 0x4b800000, v20
	s_nop 0
	v_cndmask_b32_e32 v20, v20, v21, vcc
	v_rsq_f32_e32 v20, v20
	s_nop 0
	v_mul_f32_e32 v21, 0x45800000, v20
	v_cndmask_b32_e32 v20, v20, v21, vcc
	v_pk_mul_f32 v[26:27], v[20:21], v[28:29] op_sel_hi:[0,1]
	v_pk_mul_f32 v[24:25], v[20:21], v[24:25] op_sel_hi:[0,1]
	v_pk_mul_f32 v[38:39], v[20:21], v[38:39] op_sel_hi:[0,1]
	v_pk_mul_f32 v[40:41], v[20:21], v[40:41] op_sel_hi:[0,1]
	v_pk_fma_f32 v[24:25], v[54:55], v[24:25], v[8:9]
	v_pk_fma_f32 v[8:9], v[56:57], v[26:27], v[6:7]
	v_pk_fma_f32 v[16:17], v[58:59], v[40:41], v[16:17]
	v_pk_fma_f32 v[14:15], v[60:61], v[38:39], v[14:15]
	s_nop 0
	v_cvt_pk_bf16_f32 v6, v14, v15
	v_cvt_pk_bf16_f32 v7, v16, v17
	v_cvt_pk_bf16_f32 v8, v8, v9
	v_cvt_pk_bf16_f32 v9, v24, v25
	global_store_dwordx4 v[22:23], v[6:9], off
	s_nop 1
	v_mov_b32_e32 v6, v33
	v_mov_b32_e32 v7, v35
	v_mov_b32_e32 v8, v37
	v_mov_b32_e32 v9, v19
	v_pk_mul_f32 v[6:7], v[20:21], v[6:7] op_sel_hi:[0,1]
	v_pk_mul_f32 v[8:9], v[20:21], v[8:9] op_sel_hi:[0,1]
	v_mov_b32_e32 v33, v34
	v_mov_b32_e32 v37, v18
	v_pk_fma_f32 v[8:9], v[66:67], v[8:9], v[12:13]
	v_pk_fma_f32 v[6:7], v[68:69], v[6:7], v[10:11]
	v_pk_mul_f32 v[10:11], v[20:21], v[32:33] op_sel_hi:[0,1]
	v_pk_mul_f32 v[12:13], v[20:21], v[36:37] op_sel_hi:[0,1]
	v_pk_fma_f32 v[12:13], v[62:63], v[12:13], v[4:5]
	v_pk_fma_f32 v[4:5], v[64:65], v[10:11], v[2:3]
	v_cvt_pk_bf16_f32 v2, v6, v7
	v_cvt_pk_bf16_f32 v3, v8, v9
	s_nop 0
	v_cvt_pk_bf16_f32 v4, v4, v5
	v_cvt_pk_bf16_f32 v5, v12, v13
	global_store_dwordx4 v[22:23], v[2:5], off offset:1024
.LBB0_242:
	s_andn2_b64 vcc, exec, s[10:11]
	s_cbranch_vccnz .LBB0_239
	v_mov_b32_e32 v2, s65
	v_mov_b32_e32 v3, s69
	v_cndmask_b32_e64 v3, v2, v3, s[0:1]
	v_mov_b32_e32 v2, s64
	v_mov_b32_e32 v6, s68
	v_ashrrev_i32_e32 v51, 31, v50
	v_add_u32_e32 v4, 0xfffffefd, v101
	v_ashrrev_i32_e32 v5, 31, v99
	v_cndmask_b32_e64 v2, v2, v6, s[0:1]
	v_cndmask_b32_e64 v6, 23, 20, s[0:1]
	v_cndmask_b32_e64 v5, 0, v5, s[0:1]
	v_cndmask_b32_e64 v4, v4, v99, s[0:1]
	v_lshlrev_b64 v[6:7], v6, v[50:51]
	v_lshl_add_u64 v[2:3], v[2:3], 0, v[6:7]
	v_lshlrev_b64 v[4:5], 12, v[4:5]
	v_lshl_add_u64 v[2:3], v[2:3], 0, v[4:5]
	v_lshl_add_u64 v[2:3], v[2:3], 0, v[0:1]
	s_movk_i32 s0, 0x1000
	v_add_co_u32_e32 v4, vcc, s0, v2
	s_movk_i32 s0, 0x3000
	s_nop 0
	v_addc_co_u32_e32 v5, vcc, 0, v3, vcc
	v_add_co_u32_e32 v6, vcc, s28, v2
	global_load_dwordx4 v[78:81], v[2:3], off nt
	global_load_dwordx4 v[74:77], v[2:3], off offset:1024 nt
	global_load_dwordx4 v[70:73], v[2:3], off offset:2048 nt
	global_load_dwordx4 v[66:69], v[2:3], off offset:3072 nt
	v_addc_co_u32_e32 v7, vcc, 0, v3, vcc
	v_add_co_u32_e32 v2, vcc, s0, v2
	v_lshl_add_u64 v[30:31], v[112:113], 0, v[0:1]
	s_nop 0
	v_addc_co_u32_e32 v3, vcc, 0, v3, vcc
	v_lshl_add_u64 v[26:27], v[110:111], 0, v[0:1]
	global_load_dwordx4 v[62:65], v[6:7], off offset:-4096 nt
	global_load_dwordx4 v[58:61], v[4:5], off offset:1024 nt
	global_load_dwordx4 v[54:57], v[4:5], off offset:2048 nt
	global_load_dwordx4 v[50:53], v[4:5], off offset:3072 nt
	global_load_dwordx4 v[46:49], v[6:7], off nt
	global_load_dwordx4 v[42:45], v[6:7], off offset:1024 nt
	global_load_dwordx4 v[38:41], v[6:7], off offset:2048 nt
	global_load_dwordx4 v[34:37], v[6:7], off offset:3072 nt
	global_load_dwordx4 v[14:17], v[2:3], off nt
	global_load_dwordx4 v[10:13], v[2:3], off offset:1024 nt
	s_nop 0
	global_load_dwordx4 v[6:9], v[2:3], off offset:2048 nt
	s_nop 0
	global_load_dwordx4 v[2:5], v[2:3], off offset:3072 nt
	s_nop 0
	global_load_dwordx4 v[22:25], v[88:89], off
	global_load_dwordx4 v[18:21], v[30:31], off
	v_mov_b32_e32 v99, v1
	global_load_dwordx4 v[26:29], v[26:27], off
	v_lshl_add_u64 v[32:33], v[110:111], 0, v[98:99]
	v_mov_b32_e32 v101, v1
	v_mov_b32_e32 v103, v1
	v_cmp_lt_i32_e32 vcc, v228, v225
	v_lshlrev_b64 v[108:109], 11, v[108:109]
	s_waitcnt vmcnt(16)
	v_mov_b32_e32 v132, v71
	s_waitcnt vmcnt(15)
	v_mov_b32_e32 v133, v67
	v_pk_mul_f32 v[132:133], v[132:133], v[132:133]
	v_cndmask_b32_e32 v95, v224, v228, vcc
	v_cmp_lt_i32_e32 vcc, v227, v225
	s_waitcnt vmcnt(0)
	v_pk_add_f32 v[28:29], v[28:29], 1.0 op_sel_hi:[1,0]
	v_pk_add_f32 v[26:27], v[26:27], 1.0 op_sel_hi:[1,0]
	v_pk_mul_f32 v[112:113], v[24:25], v[28:29]
	v_pk_mul_f32 v[114:115], v[22:23], v[26:27]
	global_load_dwordx4 v[26:29], v[88:89], off offset:1024
	global_load_dwordx4 v[22:25], v[30:31], off offset:1024
	global_load_dwordx4 v[116:119], v[32:33], off
	s_waitcnt vmcnt(0)
	v_pk_add_f32 v[32:33], v[118:119], 1.0 op_sel_hi:[1,0]
	v_pk_add_f32 v[118:119], v[116:117], 1.0 op_sel_hi:[1,0]
	v_pk_mul_f32 v[116:117], v[28:29], v[32:33]
	v_lshl_add_u64 v[32:33], v[110:111], 0, v[100:101]
	v_pk_mul_f32 v[118:119], v[26:27], v[118:119]
	global_load_dwordx4 v[122:125], v[88:89], off offset:2048
	global_load_dwordx4 v[26:29], v[30:31], off offset:2048
	global_load_dwordx4 v[126:129], v[32:33], off
	v_lshl_add_u64 v[110:111], v[110:111], 0, v[102:103]
	s_waitcnt vmcnt(0)
	v_pk_add_f32 v[32:33], v[128:129], 1.0 op_sel_hi:[1,0]
	v_pk_add_f32 v[126:127], v[126:127], 1.0 op_sel_hi:[1,0]
	v_pk_mul_f32 v[120:121], v[124:125], v[32:33]
	v_pk_mul_f32 v[122:123], v[122:123], v[126:127]
	global_load_dwordx4 v[124:127], v[88:89], off offset:3072
	s_nop 0
	global_load_dwordx4 v[30:33], v[30:31], off offset:3072
	s_nop 0
	global_load_dwordx4 v[128:131], v[110:111], off
	s_waitcnt vmcnt(0)
	v_pk_add_f32 v[110:111], v[130:131], 1.0 op_sel_hi:[1,0]
	v_pk_add_f32 v[128:129], v[128:129], 1.0 op_sel_hi:[1,0]
	v_mov_b32_e32 v130, v79
	v_mov_b32_e32 v131, v75
	v_pk_mul_f32 v[124:125], v[124:125], v[128:129]
	v_mov_b32_e32 v128, v78
	v_mov_b32_e32 v129, v74
	v_pk_mul_f32 v[130:131], v[130:131], v[130:131]
	v_pk_mul_f32 v[110:111], v[126:127], v[110:111]
	v_pk_fma_f32 v[128:129], v[128:129], v[128:129], v[130:131]
	v_mov_b32_e32 v130, v80
	v_mov_b32_e32 v131, v76
	v_pk_fma_f32 v[128:129], v[130:131], v[130:131], v[128:129]
	v_mov_b32_e32 v130, v81
	v_mov_b32_e32 v131, v77
	v_pk_fma_f32 v[128:129], v[130:131], v[130:131], v[128:129]
	v_mov_b32_e32 v130, v70
	v_mov_b32_e32 v131, v66
	v_pk_fma_f32 v[130:131], v[130:131], v[130:131], v[132:133]
	v_mov_b32_e32 v132, v72
	v_mov_b32_e32 v133, v68
	v_pk_fma_f32 v[130:131], v[132:133], v[132:133], v[130:131]
	v_mov_b32_e32 v132, v73
	v_mov_b32_e32 v133, v69
	v_pk_fma_f32 v[130:131], v[132:133], v[132:133], v[130:131]
	v_add_f32_e32 v127, v128, v129
	v_add_f32_e32 v127, v127, v130
	v_lshlrev_b32_e32 v126, 2, v95
	v_add_f32_e32 v127, v127, v131
	ds_bpermute_b32 v128, v126, v127
	v_cndmask_b32_e32 v95, v224, v227, vcc
	v_lshlrev_b32_e32 v103, 2, v95
	v_cmp_lt_i32_e32 vcc, v226, v225
	s_waitcnt lgkmcnt(0)
	v_add_f32_e32 v127, v127, v128
	ds_bpermute_b32 v128, v103, v127
	v_cndmask_b32_e32 v95, v224, v226, vcc
	v_lshlrev_b32_e32 v101, 2, v95
	v_xor_b32_e32 v95, 4, v224
	v_cmp_lt_i32_e32 vcc, v95, v225
	s_waitcnt lgkmcnt(0)
	v_add_f32_e32 v127, v127, v128
	ds_bpermute_b32 v128, v101, v127
	v_cndmask_b32_e32 v95, v224, v95, vcc
	v_lshlrev_b32_e32 v99, 2, v95
	v_xor_b32_e32 v95, 2, v224
	v_cmp_lt_i32_e32 vcc, v95, v225
	s_waitcnt lgkmcnt(0)
	v_add_f32_e32 v127, v127, v128
	ds_bpermute_b32 v128, v99, v127
	v_cndmask_b32_e32 v95, v224, v95, vcc
	v_lshlrev_b32_e32 v97, 2, v95
	v_xor_b32_e32 v95, 1, v224
	v_cmp_lt_i32_e32 vcc, v95, v225
	s_waitcnt lgkmcnt(0)
	v_add_f32_e32 v127, v127, v128
	ds_bpermute_b32 v128, v97, v127
	v_cndmask_b32_e32 v95, v224, v95, vcc
	v_lshlrev_b32_e32 v95, 2, v95
	s_waitcnt lgkmcnt(0)
	v_add_f32_e32 v127, v127, v128
	ds_bpermute_b32 v128, v95, v127
	s_waitcnt lgkmcnt(0)
	v_add_f32_e32 v127, v127, v128
	v_fmamk_f32 v127, v127, 0x3a800000, v220
	v_cmp_gt_f32_e32 vcc, s93, v127
	v_mul_f32_e32 v128, 0x4b800000, v127
	s_nop 0
	v_cndmask_b32_e32 v127, v127, v128, vcc
	v_rsq_f32_e32 v127, v127
	s_nop 0
	v_mul_f32_e32 v128, 0x45800000, v127
	v_cndmask_b32_e32 v128, v127, v128, vcc
	v_pk_mul_f32 v[78:79], v[78:79], v[128:129] op_sel_hi:[1,0]
	v_pk_mul_f32 v[80:81], v[80:81], v[128:129] op_sel_hi:[1,0]
	v_pk_fma_f32 v[78:79], v[114:115], v[78:79], v[18:19]
	v_pk_fma_f32 v[80:81], v[112:113], v[80:81], v[20:21]
	v_pk_mul_f32 v[74:75], v[74:75], v[128:129] op_sel_hi:[1,0]
	v_pk_mul_f32 v[70:71], v[70:71], v[128:129] op_sel_hi:[1,0]
	v_pk_mul_f32 v[66:67], v[66:67], v[128:129] op_sel_hi:[1,0]
	v_pk_mul_f32 v[68:69], v[68:69], v[128:129] op_sel_hi:[1,0]
	v_cvt_pk_bf16_f32 v78, v78, v79
	v_cvt_pk_bf16_f32 v79, v80, v81
	v_lshl_add_u64 v[80:81], v[90:91], 0, v[108:109]
	v_pk_mul_f32 v[76:77], v[76:77], v[128:129] op_sel_hi:[1,0]
	v_pk_fma_f32 v[74:75], v[118:119], v[74:75], v[22:23]
	v_pk_mul_f32 v[72:73], v[72:73], v[128:129] op_sel_hi:[1,0]
	v_pk_fma_f32 v[70:71], v[122:123], v[70:71], v[26:27]
	v_pk_fma_f32 v[68:69], v[110:111], v[68:69], v[32:33]
	v_pk_fma_f32 v[66:67], v[124:125], v[66:67], v[30:31]
	global_store_dwordx2 v[80:81], v[78:79], off
	v_pk_fma_f32 v[76:77], v[116:117], v[76:77], v[24:25]
	v_cvt_pk_bf16_f32 v74, v74, v75
	v_pk_fma_f32 v[72:73], v[120:121], v[72:73], v[28:29]
	v_cvt_pk_bf16_f32 v75, v76, v77
	global_store_dwordx2 v[80:81], v[74:75], off offset:512
	v_cvt_pk_bf16_f32 v70, v70, v71
	v_cvt_pk_bf16_f32 v71, v72, v73
	global_store_dwordx2 v[80:81], v[70:71], off offset:1024
	v_cvt_pk_bf16_f32 v66, v66, v67
	v_cvt_pk_bf16_f32 v67, v68, v69
	v_mov_b32_e32 v68, v63
	v_mov_b32_e32 v69, v59
	global_store_dwordx2 v[80:81], v[66:67], off offset:1536
	v_mov_b32_e32 v66, v62
	v_mov_b32_e32 v67, v58
	v_pk_mul_f32 v[68:69], v[68:69], v[68:69]
	v_mov_b32_e32 v70, v55
	v_pk_fma_f32 v[66:67], v[66:67], v[66:67], v[68:69]
	v_mov_b32_e32 v68, v64
	v_mov_b32_e32 v69, v60
	v_pk_fma_f32 v[66:67], v[68:69], v[68:69], v[66:67]
	v_mov_b32_e32 v68, v65
	v_mov_b32_e32 v69, v61
	v_mov_b32_e32 v71, v51
	v_pk_fma_f32 v[66:67], v[68:69], v[68:69], v[66:67]
	v_mov_b32_e32 v68, v54
	v_mov_b32_e32 v69, v50
	v_pk_mul_f32 v[70:71], v[70:71], v[70:71]
	v_add_f32_e32 v66, v66, v67
	v_pk_fma_f32 v[68:69], v[68:69], v[68:69], v[70:71]
	v_mov_b32_e32 v70, v56
	v_mov_b32_e32 v71, v52
	v_pk_fma_f32 v[68:69], v[70:71], v[70:71], v[68:69]
	v_mov_b32_e32 v70, v57
	v_mov_b32_e32 v71, v53
	v_pk_fma_f32 v[68:69], v[70:71], v[70:71], v[68:69]
	s_nop 0
	v_add_f32_e32 v66, v66, v68
	v_add_f32_e32 v66, v66, v69
	ds_bpermute_b32 v67, v126, v66
	v_lshlrev_b64 v[68:69], 11, v[106:107]
	s_waitcnt lgkmcnt(0)
	v_add_f32_e32 v66, v66, v67
	ds_bpermute_b32 v67, v103, v66
	s_waitcnt lgkmcnt(0)
	v_add_f32_e32 v66, v66, v67
	ds_bpermute_b32 v67, v101, v66
	s_waitcnt lgkmcnt(0)
	v_add_f32_e32 v66, v66, v67
	ds_bpermute_b32 v67, v99, v66
	s_waitcnt lgkmcnt(0)
	v_add_f32_e32 v66, v66, v67
	ds_bpermute_b32 v67, v97, v66
	s_waitcnt lgkmcnt(0)
	v_add_f32_e32 v66, v66, v67
	ds_bpermute_b32 v67, v95, v66
	s_waitcnt lgkmcnt(0)
	v_add_f32_e32 v66, v66, v67
	v_fmamk_f32 v66, v66, 0x3a800000, v220
	v_cmp_gt_f32_e32 vcc, s93, v66
	v_mul_f32_e32 v67, 0x4b800000, v66
	s_nop 0
	v_cndmask_b32_e32 v66, v66, v67, vcc
	v_rsq_f32_e32 v66, v66
	s_nop 0
	v_mul_f32_e32 v67, 0x45800000, v66
	v_cndmask_b32_e32 v66, v66, v67, vcc
	v_pk_mul_f32 v[62:63], v[62:63], v[66:67] op_sel_hi:[1,0]
	v_pk_mul_f32 v[64:65], v[64:65], v[66:67] op_sel_hi:[1,0]
	v_pk_fma_f32 v[62:63], v[114:115], v[62:63], v[18:19]
	v_pk_fma_f32 v[64:65], v[112:113], v[64:65], v[20:21]
	v_pk_mul_f32 v[58:59], v[58:59], v[66:67] op_sel_hi:[1,0]
	v_pk_mul_f32 v[54:55], v[54:55], v[66:67] op_sel_hi:[1,0]
	v_pk_mul_f32 v[50:51], v[50:51], v[66:67] op_sel_hi:[1,0]
	v_pk_mul_f32 v[52:53], v[52:53], v[66:67] op_sel_hi:[1,0]
	v_cvt_pk_bf16_f32 v62, v62, v63
	v_cvt_pk_bf16_f32 v63, v64, v65
	v_lshl_add_u64 v[64:65], v[90:91], 0, v[68:69]
	v_pk_mul_f32 v[60:61], v[60:61], v[66:67] op_sel_hi:[1,0]
	v_pk_fma_f32 v[58:59], v[118:119], v[58:59], v[22:23]
	v_pk_mul_f32 v[56:57], v[56:57], v[66:67] op_sel_hi:[1,0]
	v_pk_fma_f32 v[54:55], v[122:123], v[54:55], v[26:27]
	v_pk_fma_f32 v[52:53], v[110:111], v[52:53], v[32:33]
	v_pk_fma_f32 v[50:51], v[124:125], v[50:51], v[30:31]
	global_store_dwordx2 v[64:65], v[62:63], off
	v_pk_fma_f32 v[60:61], v[116:117], v[60:61], v[24:25]
	v_cvt_pk_bf16_f32 v58, v58, v59
	v_pk_fma_f32 v[56:57], v[120:121], v[56:57], v[28:29]
	v_cvt_pk_bf16_f32 v59, v60, v61
	global_store_dwordx2 v[64:65], v[58:59], off offset:512
	v_cvt_pk_bf16_f32 v54, v54, v55
	v_cvt_pk_bf16_f32 v55, v56, v57
	global_store_dwordx2 v[64:65], v[54:55], off offset:1024
	v_cvt_pk_bf16_f32 v50, v50, v51
	v_cvt_pk_bf16_f32 v51, v52, v53
	v_mov_b32_e32 v52, v47
	v_mov_b32_e32 v53, v43
	global_store_dwordx2 v[64:65], v[50:51], off offset:1536
	v_mov_b32_e32 v50, v46
	v_mov_b32_e32 v51, v42
	v_pk_mul_f32 v[52:53], v[52:53], v[52:53]
	v_mov_b32_e32 v54, v39
	v_pk_fma_f32 v[50:51], v[50:51], v[50:51], v[52:53]
	v_mov_b32_e32 v52, v48
	v_mov_b32_e32 v53, v44
	v_pk_fma_f32 v[50:51], v[52:53], v[52:53], v[50:51]
	v_mov_b32_e32 v52, v49
	v_mov_b32_e32 v53, v45
	v_mov_b32_e32 v55, v35
	v_pk_fma_f32 v[50:51], v[52:53], v[52:53], v[50:51]
	v_mov_b32_e32 v52, v38
	v_mov_b32_e32 v53, v34
	v_pk_mul_f32 v[54:55], v[54:55], v[54:55]
	v_add_f32_e32 v50, v50, v51
	v_pk_fma_f32 v[52:53], v[52:53], v[52:53], v[54:55]
	v_mov_b32_e32 v54, v40
	v_mov_b32_e32 v55, v36
	v_pk_fma_f32 v[52:53], v[54:55], v[54:55], v[52:53]
	v_mov_b32_e32 v54, v41
	v_mov_b32_e32 v55, v37
	v_pk_fma_f32 v[52:53], v[54:55], v[54:55], v[52:53]
	s_nop 0
	v_add_f32_e32 v50, v50, v52
	v_add_f32_e32 v50, v50, v53
	ds_bpermute_b32 v51, v126, v50
	v_lshlrev_b64 v[52:53], 11, v[104:105]
	s_waitcnt lgkmcnt(0)
	v_add_f32_e32 v50, v50, v51
	ds_bpermute_b32 v51, v103, v50
	s_waitcnt lgkmcnt(0)
	v_add_f32_e32 v50, v50, v51
	ds_bpermute_b32 v51, v101, v50
	s_waitcnt lgkmcnt(0)
	v_add_f32_e32 v50, v50, v51
	ds_bpermute_b32 v51, v99, v50
	s_waitcnt lgkmcnt(0)
	v_add_f32_e32 v50, v50, v51
	ds_bpermute_b32 v51, v97, v50
	s_waitcnt lgkmcnt(0)
	v_add_f32_e32 v50, v50, v51
	ds_bpermute_b32 v51, v95, v50
	s_waitcnt lgkmcnt(0)
	v_add_f32_e32 v50, v50, v51
	v_fmamk_f32 v50, v50, 0x3a800000, v220
	v_cmp_gt_f32_e32 vcc, s93, v50
	v_mul_f32_e32 v51, 0x4b800000, v50
	s_nop 0
	v_cndmask_b32_e32 v50, v50, v51, vcc
	v_rsq_f32_e32 v50, v50
	s_nop 0
	v_mul_f32_e32 v51, 0x45800000, v50
	v_cndmask_b32_e32 v50, v50, v51, vcc
	v_pk_mul_f32 v[46:47], v[46:47], v[50:51] op_sel_hi:[1,0]
	v_pk_mul_f32 v[48:49], v[48:49], v[50:51] op_sel_hi:[1,0]
	v_pk_fma_f32 v[46:47], v[114:115], v[46:47], v[18:19]
	v_pk_fma_f32 v[48:49], v[112:113], v[48:49], v[20:21]
	v_pk_mul_f32 v[42:43], v[42:43], v[50:51] op_sel_hi:[1,0]
	v_pk_mul_f32 v[38:39], v[38:39], v[50:51] op_sel_hi:[1,0]
	v_pk_mul_f32 v[34:35], v[34:35], v[50:51] op_sel_hi:[1,0]
	v_pk_mul_f32 v[36:37], v[36:37], v[50:51] op_sel_hi:[1,0]
	v_cvt_pk_bf16_f32 v46, v46, v47
	v_cvt_pk_bf16_f32 v47, v48, v49
	v_lshl_add_u64 v[48:49], v[90:91], 0, v[52:53]
	v_pk_mul_f32 v[44:45], v[44:45], v[50:51] op_sel_hi:[1,0]
	v_pk_fma_f32 v[42:43], v[118:119], v[42:43], v[22:23]
	v_pk_mul_f32 v[40:41], v[40:41], v[50:51] op_sel_hi:[1,0]
	v_pk_fma_f32 v[38:39], v[122:123], v[38:39], v[26:27]
	v_pk_fma_f32 v[36:37], v[110:111], v[36:37], v[32:33]
	v_pk_fma_f32 v[34:35], v[124:125], v[34:35], v[30:31]
	global_store_dwordx2 v[48:49], v[46:47], off
	v_pk_fma_f32 v[44:45], v[116:117], v[44:45], v[24:25]
	v_cvt_pk_bf16_f32 v42, v42, v43
	v_pk_fma_f32 v[40:41], v[120:121], v[40:41], v[28:29]
	v_cvt_pk_bf16_f32 v43, v44, v45
	global_store_dwordx2 v[48:49], v[42:43], off offset:512
	v_cvt_pk_bf16_f32 v38, v38, v39
	v_cvt_pk_bf16_f32 v39, v40, v41
	global_store_dwordx2 v[48:49], v[38:39], off offset:1024
	v_cvt_pk_bf16_f32 v34, v34, v35
	v_cvt_pk_bf16_f32 v35, v36, v37
	v_mov_b32_e32 v36, v15
	v_mov_b32_e32 v37, v11
	global_store_dwordx2 v[48:49], v[34:35], off offset:1536
	v_mov_b32_e32 v34, v14
	v_mov_b32_e32 v35, v10
	v_pk_mul_f32 v[36:37], v[36:37], v[36:37]
	v_mov_b32_e32 v38, v7
	v_pk_fma_f32 v[34:35], v[34:35], v[34:35], v[36:37]
	v_mov_b32_e32 v36, v16
	v_mov_b32_e32 v37, v12
	v_pk_fma_f32 v[34:35], v[36:37], v[36:37], v[34:35]
	v_mov_b32_e32 v36, v17
	v_mov_b32_e32 v37, v13
	v_mov_b32_e32 v39, v3
	v_pk_fma_f32 v[34:35], v[36:37], v[36:37], v[34:35]
	v_mov_b32_e32 v36, v6
	v_mov_b32_e32 v37, v2
	v_pk_mul_f32 v[38:39], v[38:39], v[38:39]
	v_add_f32_e32 v34, v34, v35
	v_pk_fma_f32 v[36:37], v[36:37], v[36:37], v[38:39]
	v_mov_b32_e32 v38, v8
	v_mov_b32_e32 v39, v4
	v_pk_fma_f32 v[36:37], v[38:39], v[38:39], v[36:37]
	v_mov_b32_e32 v38, v9
	v_mov_b32_e32 v39, v5
	v_pk_fma_f32 v[36:37], v[38:39], v[38:39], v[36:37]
	s_nop 0
	v_add_f32_e32 v34, v34, v36
	v_add_f32_e32 v34, v34, v37
	ds_bpermute_b32 v35, v126, v34
	v_lshlrev_b64 v[36:37], 11, v[92:93]
	s_waitcnt lgkmcnt(0)
	v_add_f32_e32 v34, v34, v35
	ds_bpermute_b32 v35, v103, v34
	s_waitcnt lgkmcnt(0)
	v_add_f32_e32 v34, v34, v35
	ds_bpermute_b32 v35, v101, v34
	s_waitcnt lgkmcnt(0)
	v_add_f32_e32 v34, v34, v35
	ds_bpermute_b32 v35, v99, v34
	s_waitcnt lgkmcnt(0)
	v_add_f32_e32 v34, v34, v35
	ds_bpermute_b32 v35, v97, v34
	s_waitcnt lgkmcnt(0)
	v_add_f32_e32 v34, v34, v35
	ds_bpermute_b32 v35, v95, v34
	s_waitcnt lgkmcnt(0)
	v_add_f32_e32 v34, v34, v35
	v_fmamk_f32 v34, v34, 0x3a800000, v220
	v_cmp_gt_f32_e32 vcc, s93, v34
	v_mul_f32_e32 v35, 0x4b800000, v34
	s_nop 0
	v_cndmask_b32_e32 v34, v34, v35, vcc
	v_rsq_f32_e32 v34, v34
	s_nop 0
	v_mul_f32_e32 v35, 0x45800000, v34
	v_cndmask_b32_e32 v34, v34, v35, vcc
	v_pk_mul_f32 v[14:15], v[14:15], v[34:35] op_sel_hi:[1,0]
	v_pk_mul_f32 v[16:17], v[16:17], v[34:35] op_sel_hi:[1,0]
	v_pk_fma_f32 v[14:15], v[114:115], v[14:15], v[18:19]
	v_pk_fma_f32 v[16:17], v[112:113], v[16:17], v[20:21]
	v_pk_mul_f32 v[10:11], v[10:11], v[34:35] op_sel_hi:[1,0]
	v_pk_mul_f32 v[6:7], v[6:7], v[34:35] op_sel_hi:[1,0]
	v_pk_mul_f32 v[2:3], v[2:3], v[34:35] op_sel_hi:[1,0]
	v_cvt_pk_bf16_f32 v14, v14, v15
	v_cvt_pk_bf16_f32 v15, v16, v17
	v_lshl_add_u64 v[16:17], v[90:91], 0, v[36:37]
	v_pk_mul_f32 v[12:13], v[12:13], v[34:35] op_sel_hi:[1,0]
	v_pk_fma_f32 v[10:11], v[118:119], v[10:11], v[22:23]
	v_pk_mul_f32 v[8:9], v[8:9], v[34:35] op_sel_hi:[1,0]
	v_pk_fma_f32 v[6:7], v[122:123], v[6:7], v[26:27]
	v_pk_mul_f32 v[4:5], v[4:5], v[34:35] op_sel_hi:[1,0]
	v_pk_fma_f32 v[2:3], v[124:125], v[2:3], v[30:31]
	global_store_dwordx2 v[16:17], v[14:15], off
	v_pk_fma_f32 v[12:13], v[116:117], v[12:13], v[24:25]
	v_cvt_pk_bf16_f32 v10, v10, v11
	v_pk_fma_f32 v[8:9], v[120:121], v[8:9], v[28:29]
	v_cvt_pk_bf16_f32 v11, v12, v13
	global_store_dwordx2 v[16:17], v[10:11], off offset:512
	v_cvt_pk_bf16_f32 v6, v6, v7
	v_cvt_pk_bf16_f32 v7, v8, v9
	global_store_dwordx2 v[16:17], v[6:7], off offset:1024
	v_pk_fma_f32 v[4:5], v[110:111], v[4:5], v[32:33]
	v_cvt_pk_bf16_f32 v2, v2, v3
	s_nop 0
	v_cvt_pk_bf16_f32 v3, v4, v5
	global_store_dwordx2 v[16:17], v[2:3], off offset:1536
	s_branch .LBB0_239
